# v16 + static s_setprio 1 for waves 4-7 during the attention phase (younger-half priority raise, reset at phase exit)
# baseline (speedup 1.0000x reference)
.LBB0_492:
	v_readfirstlane_b32 s0, v210
	s_nop 3
	s_lshr_b32 s0, s0, 6
	s_cmp_ge_u32 s0, 4
	s_cbranch_scc0 .Lattn_prio_done
	s_setprio 1

.LBB0_709:
	s_setprio 0
	s_load_dwordx2 s[36:37], s[74:75], 0x98
	s_waitcnt lgkmcnt(0)
	s_waitcnt vmcnt(0)
	v_mov_b32_e32 v0, v210
	s_barrier
	s_nop 0
	v_cmp_eq_u32_e32 vcc, 0, v0
	s_and_saveexec_b64 s[34:35], vcc
	s_cbranch_execz .LBB0_753
	v_mov_b32_e32 v0, s91
	s_getreg_b32 s0, hwreg(HW_REG_XCC_ID, 0, 4)
	s_waitcnt vmcnt(0) expcnt(0) lgkmcnt(0)
	ds_read_b32 v2, v0
	v_readlane_b32 s1, v255, 0
	s_and_b32 s0, s0, 15
	s_waitcnt lgkmcnt(0)
	v_cmp_ne_u32_e32 vcc, 0, v2
	v_mov_b32_e32 v0, s1
	ds_read_b32 v0, v0
	s_cbranch_vccnz .LBB0_724
	s_add_u32 s2, s36, 0x1200
	s_addc_u32 s3, s37, 0
	s_add_u32 s4, s36, 0x1400
	s_addc_u32 s5, s37, 0
	s_add_u32 s6, s36, 0x1500
	s_addc_u32 s7, s37, 0
	s_add_u32 s8, s36, 0x1600
	s_addc_u32 s9, s37, 0
	s_add_u32 s10, s36, 0x1700
	s_addc_u32 s11, s37, 0
	s_add_u32 s12, s36, 0x1800
	s_addc_u32 s13, s37, 0
	s_add_u32 s14, s36, 0x1900
	s_addc_u32 s15, s37, 0
	s_add_u32 s16, s36, 0x1a00
	s_addc_u32 s17, s37, 0
	s_add_u32 s18, s36, 0x1b00
	s_addc_u32 s19, s37, 0
	s_add_u32 s20, s36, 0x1c00
	s_addc_u32 s21, s37, 0
	s_add_u32 s22, s36, 0x1d00
	s_addc_u32 s23, s37, 0
	s_add_u32 s24, s36, 0x1e00
	s_addc_u32 s25, s37, 0
	s_add_u32 s26, s36, 0x1f00
	s_addc_u32 s27, s37, 0
	s_add_u32 s28, s36, 0x2000
	s_addc_u32 s29, s37, 0
	s_add_u32 s30, s36, 0x2100
	s_addc_u32 s31, s37, 0
	s_add_u32 s38, s36, 0x2200
	s_addc_u32 s39, s37, 0
	s_add_u32 s40, s36, 0x2300
	s_addc_u32 s41, s37, 0
	s_mov_b32 s1, 1
	s_mov_b64 s[42:43], 0
	s_branch .LBB0_714
